# dynamic mix queue: 64 long ctx-FNet items dequeued before the short SGU items (longest-first packing)
# baseline (speedup 1.0000x reference)
; __device__ __forceinline__ int tid_l() { int t = threadIdx.x; asm volatile("" : "+v"(t)); return t; }
; __device__ __forceinline__ void phase_mix(const Params& p, int l, char* smem) {
;     ...
;   for (;;) {
;     const int tid = tid_l(), wid = tid >> 6;
;     __syncthreads();
;     if (tid == 0) *s_item = atomicAdd(cnt, 1);
;     __syncthreads();
;     int it = *s_item;
;     if (it >= total) break;
;     if (it < N_GDN) {
;       gdn_block4(p, l, (it >> 2) & 31, it & 3, it >> 7, smem, ctx_out);
;     ...
;     it -= N_SC;
;     {
;       const int grp = tid >> 8, t2 = tid & 255, lane = t2 & 63, w4 = t2 >> 6, wr = w4 >> 1, wc = w4 & 1, fr = lane & 15, fq = lane >> 4;
;       const int b = it >> 1, mt = it & 1, nt = grp;
;       f32x4 acc[4][4];
;       zero_acc<4>(acc);
;       gemm_tile<4>(reinterpret_cast<const u16*>(p.ws + OFF_DC) + (size_t)mt * 128 * 512, 512,
;                    reinterpret_cast<const u16*>(p.ws + OFF_FTC) + (size_t)(b * 256 + nt * 128) * 512, 512, 512, acc, smem + grp * 32768);
.LBB0_1101:
	s_or_b64 exec, exec, s[0:1]
	s_add_i32 s0, 0, 0x25200
	s_cmp_lg_u32 s0, -1
	s_cselect_b32 s0, s0, 0
	s_cselect_b32 s1, s39, 0
	v_mov_b32_e32 v2, s0
	v_mov_b32_e32 v3, s1
	s_waitcnt lgkmcnt(0)
	s_barrier
	flat_load_dword v56, v[2:3] sc0 sc1
	s_waitcnt vmcnt(0)
	s_mov_b64 s[0:1], -1
	s_waitcnt lgkmcnt(0)
	s_cmpk_lg_i32 s83, 0xac0
	s_cbranch_scc1 .Lmix_noremap
	v_subrev_u32_e32 v2, 0x180, v56
	v_add_u32_e32 v3, 0x900, v56
	v_subrev_u32_e32 v4, 64, v56
	v_cmp_gt_u32_e32 vcc, 0x940, v2
	s_nop 1
	v_cndmask_b32_e32 v4, v56, v4, vcc
	v_cmp_gt_u32_e32 vcc, 64, v2
	s_nop 1
	v_cndmask_b32_e32 v56, v4, v3, vcc
.Lmix_noremap:
	v_cmp_gt_i32_e32 vcc, s83, v56
	s_and_saveexec_b64 s[94:95], vcc
	s_cbranch_execz .LBB0_1096
	s_movk_i32 s0, 0xff
	v_cmp_lt_i32_e32 vcc, s0, v56
	s_and_saveexec_b64 s[0:1], vcc
	s_xor_b64 s[14:15], exec, s[0:1]
	s_cbranch_execz .LBB0_1190
	s_movk_i32 s0, 0x17f
	v_cmp_lt_u32_e32 vcc, s0, v56
	s_and_saveexec_b64 s[0:1], vcc
	s_xor_b64 s[0:1], exec, s[0:1]
	s_cbranch_execz .LBB0_1118
	s_movk_i32 s2, 0x97f
	v_cmp_lt_u32_e32 vcc, s2, v56
	s_and_saveexec_b64 s[4:5], vcc
	s_xor_b64 s[4:5], exec, s[4:5]
	s_cbranch_execz .LBB0_1115
	s_movk_i32 s2, 0xa7f
	v_cmp_lt_u32_e32 vcc, s2, v56
	s_and_saveexec_b64 s[6:7], vcc
	s_xor_b64 s[6:7], exec, s[6:7]
	s_cbranch_execz .LBB0_1113
	v_and_b32_e32 v67, 1, v56
	v_readlane_b32 s8, v253, 60
	v_lshlrev_b32_e32 v2, 17, v67
	v_mov_b32_e32 v3, v0
	v_readlane_b32 s9, v253, 61
	v_ashrrev_i32_e32 v10, 8, v1
	v_lshlrev_b32_e32 v66, 7, v10
	v_lshl_add_u64 v[4:5], s[8:9], 0, v[2:3]
	v_lshlrev_b32_e32 v3, 7, v56
	v_and_b32_e32 v3, 0x7fffff00, v3
	v_add_u32_e32 v76, 0xfffac000, v3
	v_mov_b32_e32 v16, v176
	v_add_u32_e32 v6, v76, v66
	v_lshl_add_u32 v3, v10, 15, 0
	v_ashrrev_i32_e32 v7, 31, v6
	v_and_b32_e32 v17, 0xff, v16
	v_lshlrev_b32_e32 v20, 8, v16
	v_readlane_b32 s8, v253, 44
	v_and_b32_e32 v10, 0xfc00, v20
	v_mov_b32_e32 v11, v0
	v_lshlrev_b32_e32 v14, 4, v16
	v_lshl_add_u32 v77, v17, 4, v3
	v_lshlrev_b64 v[6:7], 10, v[6:7]
	v_readlane_b32 s9, v253, 45
	v_lshl_add_u64 v[12:13], v[4:5], 0, v[10:11]
	v_and_b32_e32 v14, 48, v14
	v_mov_b32_e32 v15, v0
	v_readfirstlane_b32 s2, v77
	v_lshl_add_u64 v[8:9], s[8:9], 0, v[6:7]
	v_lshl_add_u64 v[12:13], v[12:13], 0, v[14:15]
	s_mov_b32 m0, s2
	s_barrier
	global_load_lds_dwordx4 v[12:13], off
	v_lshl_add_u64 v[12:13], v[8:9], 0, v[10:11]
	v_add_u32_e32 v11, 0x2000, v77
	v_lshl_add_u64 v[12:13], v[12:13], 0, v[14:15]
	v_readfirstlane_b32 s2, v11
	s_mov_b32 m0, s2
	s_mov_b32 s2, 0x1fc00
	global_load_lds_dwordx4 v[12:13], off
	v_bitop3_b32 v12, v20, s2, v194 bitop3:0xc8
	v_mov_b32_e32 v13, v0
	v_add_u32_e32 v11, 0x1000, v77
	v_lshl_add_u64 v[4:5], v[4:5], 0, v[12:13]
	v_readfirstlane_b32 s2, v11
	v_lshl_add_u64 v[4:5], v[4:5], 0, v[14:15]
	s_mov_b32 m0, s2
	v_and_b32_e32 v18, 15, v16
	global_load_lds_dwordx4 v[4:5], off
	v_lshl_add_u64 v[4:5], v[8:9], 0, v[12:13]
	v_add_u32_e32 v8, 0x3000, v77
	v_lshl_add_u64 v[4:5], v[4:5], 0, v[14:15]
	v_readfirstlane_b32 s2, v8
	s_mov_b32 m0, s2
	v_readlane_b32 s8, v254, 60
	global_load_lds_dwordx4 v[4:5], off
	v_lshrrev_b32_e32 v4, 1, v16
	v_and_or_b32 v4, v4, 64, v18
	v_lshlrev_b32_e32 v78, 6, v4
	v_lshlrev_b32_e32 v4, 6, v16
	v_and_b32_e32 v79, 0x13c0, v4
	v_or3_b32 v4, v2, v10, v14
	v_mov_b32_e32 v5, v0
	v_readlane_b32 s9, v254, 61
	v_readlane_b32 s10, v254, 62
	v_readlane_b32 s11, v254, 63
	v_lshl_add_u64 v[68:69], s[8:9], 0, v[4:5]
	v_or3_b32 v4, v6, v10, v14
	v_mov_b32_e32 v5, v7
	v_and_b32_e32 v19, 48, v16
	v_lshl_add_u64 v[70:71], s[10:11], 0, v[4:5]
	v_or_b32_e32 v4, 0x10000, v10
	v_add_u32_e32 v80, v3, v19
	v_or3_b32 v2, v2, v4, v14
	v_mov_b32_e32 v3, v0
	v_lshl_add_u64 v[72:73], s[8:9], 0, v[2:3]
	v_or3_b32 v6, v6, v4, v14
	v_mov_b32_e32 v2, 0
	v_lshl_add_u64 v[74:75], s[10:11], 0, v[6:7]
	s_mov_b32 s2, 0
	s_mov_b64 s[8:9], 0
	v_mov_b32_e32 v3, v2
	v_mov_b32_e32 v4, v2
	v_mov_b32_e32 v5, v2
	v_mov_b32_e32 v6, v2
	v_mov_b32_e32 v7, v2
	v_mov_b32_e32 v8, v2
	v_mov_b32_e32 v9, v2
	v_mov_b32_e32 v10, v2
	v_mov_b32_e32 v11, v2
	v_mov_b32_e32 v12, v2
	v_mov_b32_e32 v13, v2
	v_mov_b32_e32 v14, v2
	v_mov_b32_e32 v15, v2
	v_mov_b32_e32 v16, v2
	v_mov_b32_e32 v17, v2
	v_mov_b32_e32 v18, v2
	v_mov_b32_e32 v19, v2
	v_mov_b32_e32 v20, v2
	v_mov_b32_e32 v21, v2
	v_mov_b32_e32 v22, v2
	v_mov_b32_e32 v23, v2
	v_mov_b32_e32 v24, v2
	v_mov_b32_e32 v25, v2
	v_mov_b32_e32 v26, v2
	v_mov_b32_e32 v27, v2
	v_mov_b32_e32 v28, v2
	v_mov_b32_e32 v29, v2
	v_mov_b32_e32 v30, v2
	v_mov_b32_e32 v31, v2
	v_mov_b32_e32 v32, v2
	v_mov_b32_e32 v33, v2
	v_mov_b32_e32 v34, v2
	v_mov_b32_e32 v35, v2
	v_mov_b32_e32 v36, v2
	v_mov_b32_e32 v37, v2
	v_mov_b32_e32 v38, v2
	v_mov_b32_e32 v39, v2
	v_mov_b32_e32 v40, v2
	v_mov_b32_e32 v41, v2
	v_mov_b32_e32 v42, v2
	v_mov_b32_e32 v43, v2
	v_mov_b32_e32 v44, v2
	v_mov_b32_e32 v45, v2
	v_mov_b32_e32 v46, v2
	v_mov_b32_e32 v47, v2
	v_mov_b32_e32 v48, v2
	v_mov_b32_e32 v49, v2
	v_mov_b32_e32 v50, v2
	v_mov_b32_e32 v51, v2
	v_mov_b32_e32 v52, v2
	v_mov_b32_e32 v53, v2
	v_mov_b32_e32 v54, v2
	v_mov_b32_e32 v55, v2
	v_mov_b32_e32 v56, v2
	v_mov_b32_e32 v57, v2
	v_mov_b32_e32 v58, v2
	v_mov_b32_e32 v59, v2
	v_mov_b32_e32 v60, v2
	v_mov_b32_e32 v61, v2
	v_mov_b32_e32 v62, v2
	v_mov_b32_e32 v63, v2
	v_mov_b32_e32 v64, v2
	v_mov_b32_e32 v65, v2
	s_branch .LBB0_1108
